# phase-0 x->bf16 shares rebalanced by workgroup class
# baseline (speedup 1.0000x reference)
.Lp0_xconv:
	s_cmp_lt_u32 s92, 48
	s_cbranch_scc0 .Lp0_x0
	s_mul_i32 s0, s92, 12
	s_mov_b32 s1, 12
	s_branch .Lp0_xgo
.Lp0_x0:
	s_cmpk_lt_u32 s92, 0x88
	s_cbranch_scc0 .Lp0_x1
	s_sub_u32 s0, s92, 48
	s_lshl_b32 s0, s0, 3
	s_add_u32 s0, s0, 576
	s_mov_b32 s1, 8
	s_branch .Lp0_xgo
.Lp0_x1:
	s_cmpk_lt_u32 s92, 0xb8
	s_cbranch_scc0 .Lp0_x2
	s_sub_u32 s0, s92, 0x88
	s_lshl_b32 s0, s0, 4
	s_add_u32 s0, s0, 1280
	s_mov_b32 s1, 16
	s_branch .Lp0_xgo
.Lp0_x2:
	s_cmpk_lt_u32 s92, 0xc8
	s_cbranch_scc0 .Lp0_x3
	s_sub_u32 s0, s92, 0xb8
	s_mul_i32 s0, s0, 20
	s_add_u32 s0, s0, 2048
	s_mov_b32 s1, 20
	s_branch .Lp0_xgo
.Lp0_x3:
	s_sub_u32 s0, s92, 0xc8
	s_lshl_b32 s0, s0, 5
	s_add_u32 s0, s0, 2368
	s_mov_b32 s1, 32
